# v72: barrier spin loops poll without the s_sleep between polls
# baseline (speedup 1.0000x reference)
.LBB0_97:
	global_load_dword v16, v17, s[6:7] sc1
	global_load_dword v1, v17, s[8:9] sc1
	global_load_dword v2, v17, s[10:11] sc1
	global_load_dword v3, v17, s[12:13] sc1
	global_load_dword v4, v17, s[14:15] sc1
	global_load_dword v5, v17, s[16:17] sc1
	global_load_dword v6, v17, s[18:19] sc1
	global_load_dword v7, v17, s[20:21] sc1
	global_load_dword v8, v17, s[22:23] sc1
	global_load_dword v9, v17, s[24:25] sc1
	global_load_dword v10, v17, s[26:27] sc1
	global_load_dword v11, v17, s[28:29] sc1
	global_load_dword v12, v17, s[30:31] sc1
	global_load_dword v13, v17, s[34:35] sc1
	global_load_dword v14, v17, s[36:37] sc1
	global_load_dword v15, v17, s[38:39] sc1
	s_mov_b64 s[40:41], -1
	s_mov_b64 s[42:43], -1
	s_waitcnt vmcnt(14)
	v_add_u32_e32 v18, v1, v16
	s_waitcnt vmcnt(13)
	v_add_u32_e32 v18, v18, v2
	s_waitcnt vmcnt(12)
	v_add_u32_e32 v18, v18, v3
	s_waitcnt vmcnt(11)
	v_add_u32_e32 v18, v18, v4
	s_waitcnt vmcnt(10)
	v_add_u32_e32 v18, v18, v5
	s_waitcnt vmcnt(9)
	v_add_u32_e32 v18, v18, v6
	s_waitcnt vmcnt(8)
	v_add_u32_e32 v18, v18, v7
	s_waitcnt vmcnt(7)
	v_add_u32_e32 v18, v18, v8
	s_waitcnt vmcnt(6)
	v_add_u32_e32 v18, v18, v9
	s_waitcnt vmcnt(5)
	v_add_u32_e32 v18, v18, v10
	s_waitcnt vmcnt(4)
	v_add_u32_e32 v18, v18, v11
	s_waitcnt vmcnt(3)
	v_add_u32_e32 v18, v18, v12
	s_waitcnt vmcnt(2)
	v_add_u32_e32 v18, v18, v13
	s_waitcnt vmcnt(1)
	v_add_u32_e32 v18, v18, v14
	s_waitcnt vmcnt(0)
	v_add_u32_e32 v18, v18, v15
	v_cmp_eq_u32_e32 vcc, s33, v18
	s_cbranch_vccnz .LBB0_96
	s_and_b32 s40, s46, 0xff
	s_cmp_eq_u32 s40, 0
	s_mov_b64 s[40:41], -1
	s_mov_b64 s[44:45], -1
	s_nop 0
	s_cbranch_scc1 .LBB0_101
	s_and_b64 vcc, exec, s[44:45]
	s_cbranch_vccz .LBB0_96

.LBB0_115:
	s_and_b32 s20, s24, 0xff
	s_mov_b64 s[18:19], -1
	s_cmp_lg_u32 s20, 0
	s_mov_b64 s[22:23], -1
	s_nop 0
	s_cbranch_scc0 .LBB0_118
	s_and_b64 vcc, exec, s[22:23]
	s_cbranch_vccz .LBB0_114

.LBB0_132:
	s_and_b32 s18, s24, 0xff
	s_cmp_lg_u32 s18, 0
	s_mov_b64 s[20:21], -1
	s_nop 0
	s_cbranch_scc0 .LBB0_135
	s_mov_b64 s[22:23], -1
	s_and_b64 vcc, exec, s[20:21]
	s_cbranch_vccz .LBB0_131

.LBB0_580:
	global_load_dword v16, v17, s[4:5] sc1
	global_load_dword v1, v17, s[6:7] sc1
	global_load_dword v2, v17, s[8:9] sc1
	global_load_dword v3, v17, s[10:11] sc1
	global_load_dword v4, v17, s[12:13] sc1
	global_load_dword v5, v17, s[14:15] sc1
	global_load_dword v6, v17, s[18:19] sc1
	global_load_dword v7, v17, s[20:21] sc1
	global_load_dword v8, v17, s[22:23] sc1
	global_load_dword v9, v17, s[24:25] sc1
	global_load_dword v10, v17, s[26:27] sc1
	global_load_dword v11, v17, s[28:29] sc1
	global_load_dword v12, v17, s[30:31] sc1
	global_load_dword v13, v17, s[34:35] sc1
	global_load_dword v14, v17, s[36:37] sc1
	global_load_dword v15, v17, s[38:39] sc1
	s_mov_b64 s[40:41], -1
	s_mov_b64 s[42:43], -1
	s_waitcnt vmcnt(14)
	v_add_u32_e32 v18, v1, v16
	s_waitcnt vmcnt(13)
	v_add_u32_e32 v18, v18, v2
	s_waitcnt vmcnt(12)
	v_add_u32_e32 v18, v18, v3
	s_waitcnt vmcnt(11)
	v_add_u32_e32 v18, v18, v4
	s_waitcnt vmcnt(10)
	v_add_u32_e32 v18, v18, v5
	s_waitcnt vmcnt(9)
	v_add_u32_e32 v18, v18, v6
	s_waitcnt vmcnt(8)
	v_add_u32_e32 v18, v18, v7
	s_waitcnt vmcnt(7)
	v_add_u32_e32 v18, v18, v8
	s_waitcnt vmcnt(6)
	v_add_u32_e32 v18, v18, v9
	s_waitcnt vmcnt(5)
	v_add_u32_e32 v18, v18, v10
	s_waitcnt vmcnt(4)
	v_add_u32_e32 v18, v18, v11
	s_waitcnt vmcnt(3)
	v_add_u32_e32 v18, v18, v12
	s_waitcnt vmcnt(2)
	v_add_u32_e32 v18, v18, v13
	s_waitcnt vmcnt(1)
	v_add_u32_e32 v18, v18, v14
	s_waitcnt vmcnt(0)
	v_add_u32_e32 v18, v18, v15
	v_cmp_eq_u32_e32 vcc, s33, v18
	s_cbranch_vccnz .LBB0_579
	s_and_b32 s40, s46, 0xff
	s_cmp_eq_u32 s40, 0
	s_mov_b64 s[40:41], -1
	s_mov_b64 s[44:45], -1
	s_nop 0
	s_cbranch_scc1 .LBB0_584
	s_and_b64 vcc, exec, s[44:45]
	s_cbranch_vccz .LBB0_579

.LBB0_1217:
	global_load_dword v16, v17, s[4:5] sc1
	global_load_dword v1, v17, s[6:7] sc1
	global_load_dword v2, v17, s[8:9] sc1
	global_load_dword v3, v17, s[10:11] sc1
	global_load_dword v4, v17, s[12:13] sc1
	global_load_dword v5, v17, s[14:15] sc1
	global_load_dword v6, v17, s[16:17] sc1
	global_load_dword v7, v17, s[18:19] sc1
	global_load_dword v8, v17, s[20:21] sc1
	global_load_dword v9, v17, s[22:23] sc1
	global_load_dword v10, v17, s[24:25] sc1
	global_load_dword v11, v17, s[26:27] sc1
	global_load_dword v12, v17, s[28:29] sc1
	global_load_dword v13, v17, s[30:31] sc1
	global_load_dword v14, v17, s[34:35] sc1
	global_load_dword v15, v17, s[36:37] sc1
	s_mov_b64 s[38:39], -1
	s_mov_b64 s[40:41], -1
	s_waitcnt vmcnt(14)
	v_add_u32_e32 v18, v1, v16
	s_waitcnt vmcnt(13)
	v_add_u32_e32 v18, v18, v2
	s_waitcnt vmcnt(12)
	v_add_u32_e32 v18, v18, v3
	s_waitcnt vmcnt(11)
	v_add_u32_e32 v18, v18, v4
	s_waitcnt vmcnt(10)
	v_add_u32_e32 v18, v18, v5
	s_waitcnt vmcnt(9)
	v_add_u32_e32 v18, v18, v6
	s_waitcnt vmcnt(8)
	v_add_u32_e32 v18, v18, v7
	s_waitcnt vmcnt(7)
	v_add_u32_e32 v18, v18, v8
	s_waitcnt vmcnt(6)
	v_add_u32_e32 v18, v18, v9
	s_waitcnt vmcnt(5)
	v_add_u32_e32 v18, v18, v10
	s_waitcnt vmcnt(4)
	v_add_u32_e32 v18, v18, v11
	s_waitcnt vmcnt(3)
	v_add_u32_e32 v18, v18, v12
	s_waitcnt vmcnt(2)
	v_add_u32_e32 v18, v18, v13
	s_waitcnt vmcnt(1)
	v_add_u32_e32 v18, v18, v14
	s_waitcnt vmcnt(0)
	v_add_u32_e32 v18, v18, v15
	v_cmp_eq_u32_e32 vcc, s33, v18
	s_cbranch_vccnz .LBB0_1216
	s_and_b32 s38, s44, 0xff
	s_cmp_eq_u32 s38, 0
	s_mov_b64 s[38:39], -1
	s_mov_b64 s[42:43], -1
	s_nop 0
	s_cbranch_scc1 .LBB0_1221
	s_and_b64 vcc, exec, s[42:43]
	s_cbranch_vccz .LBB0_1216

.LBB0_1235:
	s_and_b32 s18, s22, 0xff
	s_mov_b64 s[16:17], -1
	s_cmp_lg_u32 s18, 0
	s_mov_b64 s[20:21], -1
	s_nop 0
	s_cbranch_scc0 .LBB0_1238
	s_and_b64 vcc, exec, s[20:21]
	s_cbranch_vccz .LBB0_1234

.LBB0_1252:
	s_and_b32 s16, s22, 0xff
	s_cmp_lg_u32 s16, 0
	s_mov_b64 s[18:19], -1
	s_nop 0
	s_cbranch_scc0 .LBB0_1255
	s_mov_b64 s[20:21], -1
	s_and_b64 vcc, exec, s[18:19]
	s_cbranch_vccz .LBB0_1251

.LBB0_1841:
	global_load_dword v16, v17, s[4:5] sc1
	global_load_dword v1, v17, s[6:7] sc1
	global_load_dword v2, v17, s[8:9] sc1
	global_load_dword v3, v17, s[12:13] sc1
	global_load_dword v4, v17, s[14:15] sc1
	global_load_dword v5, v17, s[16:17] sc1
	global_load_dword v6, v17, s[18:19] sc1
	global_load_dword v7, v17, s[20:21] sc1
	global_load_dword v8, v17, s[22:23] sc1
	global_load_dword v9, v17, s[24:25] sc1
	global_load_dword v10, v17, s[26:27] sc1
	global_load_dword v11, v17, s[28:29] sc1
	global_load_dword v12, v17, s[30:31] sc1
	global_load_dword v13, v17, s[34:35] sc1
	global_load_dword v14, v17, s[36:37] sc1
	global_load_dword v15, v17, s[38:39] sc1
	s_mov_b64 s[40:41], -1
	s_mov_b64 s[42:43], -1
	s_waitcnt vmcnt(14)
	v_add_u32_e32 v18, v1, v16
	s_waitcnt vmcnt(13)
	v_add_u32_e32 v18, v18, v2
	s_waitcnt vmcnt(12)
	v_add_u32_e32 v18, v18, v3
	s_waitcnt vmcnt(11)
	v_add_u32_e32 v18, v18, v4
	s_waitcnt vmcnt(10)
	v_add_u32_e32 v18, v18, v5
	s_waitcnt vmcnt(9)
	v_add_u32_e32 v18, v18, v6
	s_waitcnt vmcnt(8)
	v_add_u32_e32 v18, v18, v7
	s_waitcnt vmcnt(7)
	v_add_u32_e32 v18, v18, v8
	s_waitcnt vmcnt(6)
	v_add_u32_e32 v18, v18, v9
	s_waitcnt vmcnt(5)
	v_add_u32_e32 v18, v18, v10
	s_waitcnt vmcnt(4)
	v_add_u32_e32 v18, v18, v11
	s_waitcnt vmcnt(3)
	v_add_u32_e32 v18, v18, v12
	s_waitcnt vmcnt(2)
	v_add_u32_e32 v18, v18, v13
	s_waitcnt vmcnt(1)
	v_add_u32_e32 v18, v18, v14
	s_waitcnt vmcnt(0)
	v_add_u32_e32 v18, v18, v15
	v_cmp_eq_u32_e32 vcc, s33, v18
	s_cbranch_vccnz .LBB0_1840
	s_and_b32 s40, s48, 0xff
	s_cmp_eq_u32 s40, 0
	s_mov_b64 s[40:41], -1
	s_mov_b64 s[44:45], -1
	s_nop 0
	s_cbranch_scc1 .LBB0_1845
	s_and_b64 vcc, exec, s[44:45]
	s_cbranch_vccz .LBB0_1840
